# row passes: streaming (nt) hint on the row loads (y and the old normalized row: last use)
# baseline (speedup 1.0000x reference)
.LBB0_520:
	s_cmp_lt_i32 s88, 4
	s_cselect_b64 s[0:1], -1, 0
	s_and_b64 s[6:7], s[0:1], s[2:3]
	s_andn2_b64 vcc, exec, s[6:7]
	s_cbranch_vccnz .LBB0_526
	s_lshl_b32 s2, s66, 3
	s_lshl_b32 s0, s66, 7
	s_and_b32 s0, s0, 0xfffff000
	s_and_b32 s1, s2, 0xf8
	s_add_i32 s3, s0, 0x1000
	s_or_b32 s4, s0, s1
	s_cmpk_eq_i32 s68, 0x100
	s_cselect_b64 s[8:9], -1, 0
	s_and_b64 s[0:1], s[8:9], exec
	s_cselect_b32 s2, s4, s2
	s_cselect_b32 s12, s3, 0x8000
	s_add_i32 s13, s2, s96
	s_cmp_ge_i32 s13, s12
	s_cbranch_scc1 .LBB0_526
	v_lshlrev_b32_e32 v14, 4, v177
	global_load_dwordx4 v[2:5], v14, s[60:61]
	global_load_dwordx4 v[6:9], v14, s[60:61] offset:1024
	global_load_dwordx4 v[10:13], v14, s[60:61] offset:2048
	s_nop 0
	global_load_dwordx4 v[14:17], v14, s[60:61] offset:3072
	v_mbcnt_lo_u32_b32 v18, -1, 0
	v_mbcnt_hi_u32_b32 v18, -1, v18
	v_and_b32_e32 v19, 64, v18
	v_add_u32_e32 v19, 64, v19
	v_xor_b32_e32 v20, 1, v18
	v_cmp_lt_i32_e32 vcc, v20, v19
	v_readlane_b32 s4, v252, 2
	s_lshl_b32 s3, s68, 3
	v_cndmask_b32_e32 v20, v18, v20, vcc
	v_lshlrev_b32_e32 v26, 2, v20
	v_xor_b32_e32 v20, 2, v18
	v_cmp_lt_i32_e32 vcc, v20, v19
	v_readlane_b32 s5, v252, 3
	s_and_b64 s[0:1], s[8:9], exec
	v_cndmask_b32_e32 v20, v18, v20, vcc
	v_lshlrev_b32_e32 v27, 2, v20
	v_xor_b32_e32 v20, 4, v18
	v_cmp_lt_i32_e32 vcc, v20, v19
	s_cselect_b32 s14, 0x100, s3
	s_lshl_b32 s3, s66, 8
	v_cndmask_b32_e32 v20, v18, v20, vcc
	v_lshlrev_b32_e32 v28, 2, v20
	v_xor_b32_e32 v20, 8, v18
	v_cmp_lt_i32_e32 vcc, v20, v19
	s_and_b32 s3, s3, 0xffffe000
	s_add_i32 s3, s96, s3
	v_cndmask_b32_e32 v20, v18, v20, vcc
	v_lshlrev_b32_e32 v29, 2, v20
	v_xor_b32_e32 v20, 16, v18
	v_cmp_lt_i32_e32 vcc, v20, v19
	v_cmp_eq_u32_e64 s[0:1], 0, v177
	s_mov_b32 s16, 0xffff0000
	v_cndmask_b32_e32 v20, v18, v20, vcc
	v_lshlrev_b32_e32 v30, 2, v20
	v_xor_b32_e32 v20, 32, v18
	v_cmp_lt_i32_e32 vcc, v20, v19
	v_mov_b32_e32 v19, 0
	v_mov_b32_e32 v32, 0x358637bd
	v_cndmask_b32_e32 v18, v18, v20, vcc
	v_lshlrev_b32_e32 v31, 2, v18
	v_lshlrev_b32_e32 v18, 3, v177
	v_lshl_add_u64 v[20:21], s[4:5], 0, v[18:19]
	v_readlane_b32 s4, v253, 52
	v_readlane_b32 s5, v253, 53
	s_mov_b32 s17, 0xf800000
	v_mov_b32_e32 v33, 0x260
	v_lshl_add_u64 v[22:23], s[4:5], 0, v[18:19]
	s_and_b32 s4, s66, 31
	s_lshl_b32 s4, s4, 4
	s_add_i32 s3, s3, s4
	s_sub_i32 s2, s3, s2
	s_add_i32 s15, s2, 0xf00
	s_movk_i32 s18, 0x7fff
	s_and_b64 s[2:3], s[8:9], exec
	s_cselect_b32 s2, s15, s13
	s_ashr_i32 s3, s2, 31
	s_lshl_b64 s[4:5], s[2:3], 11
	v_lshl_add_u64 v[98:99], v[20:21], 0, s[4:5]
	v_lshl_add_u64 v[100:101], v[22:23], 0, s[4:5]
	s_lshl_b64 s[2:3], s[2:3], 2
	s_add_u32 s2, s75, s2
	s_addc_u32 s3, s69, s3
	global_load_dwordx2 v[80:81], v[98:99], off nt
	global_load_dwordx2 v[82:83], v[98:99], off offset:512 nt
	global_load_dwordx2 v[84:85], v[98:99], off offset:1024 nt
	global_load_dwordx2 v[86:87], v[98:99], off offset:1536 nt
	global_load_dwordx2 v[88:89], v[100:101], off nt
	global_load_dwordx2 v[90:91], v[100:101], off offset:512 nt
	global_load_dwordx2 v[92:93], v[100:101], off offset:1024 nt
	global_load_dwordx2 v[94:95], v[100:101], off offset:1536 nt
	global_load_dword v96, v19, s[2:3]
	s_waitcnt vmcnt(0)
	s_branch .Lrp1_body

.Lrp1_body:
	v_mov_b32_e32 v34, v80
	v_mov_b32_e32 v35, v81
	v_mov_b32_e32 v36, v82
	v_mov_b32_e32 v37, v83
	v_mov_b32_e32 v38, v84
	v_mov_b32_e32 v39, v85
	v_mov_b32_e32 v40, v86
	v_mov_b32_e32 v41, v87
	v_mov_b32_e32 v42, v88
	v_mov_b32_e32 v43, v89
	v_mov_b32_e32 v44, v90
	v_mov_b32_e32 v45, v91
	v_mov_b32_e32 v46, v92
	v_mov_b32_e32 v47, v93
	v_mov_b32_e32 v48, v94
	v_mov_b32_e32 v49, v95
	v_mov_b32_e32 v18, v96
	s_and_b64 s[2:3], s[8:9], exec
	s_cselect_b32 s2, s15, s13
	s_ashr_i32 s3, s2, 31
	s_lshl_b64 s[4:5], s[2:3], 11
	s_lshl_b64 s[2:3], s[2:3], 2
	s_add_u32 s10, s75, s2
	v_lshl_add_u64 v[24:25], v[22:23], 0, s[4:5]
	s_addc_u32 s11, s69, s3
	s_add_i32 s2, s13, s14
	s_cmp_lt_i32 s2, s12
	s_cbranch_scc0 .Lrp1_skip
	s_sub_i32 s3, s15, s14
	s_and_b64 s[4:5], s[8:9], exec
	s_cselect_b32 s2, s3, s2
	s_ashr_i32 s3, s2, 31
	s_lshl_b64 s[4:5], s[2:3], 11
	v_lshl_add_u64 v[98:99], v[20:21], 0, s[4:5]
	v_lshl_add_u64 v[100:101], v[22:23], 0, s[4:5]
	s_lshl_b64 s[2:3], s[2:3], 2
	s_add_u32 s2, s75, s2
	s_addc_u32 s3, s69, s3
	global_load_dwordx2 v[80:81], v[98:99], off nt
	global_load_dwordx2 v[82:83], v[98:99], off offset:512 nt
	global_load_dwordx2 v[84:85], v[98:99], off offset:1024 nt
	global_load_dwordx2 v[86:87], v[98:99], off offset:1536 nt
	global_load_dwordx2 v[88:89], v[100:101], off nt
	global_load_dwordx2 v[90:91], v[100:101], off offset:512 nt
	global_load_dwordx2 v[92:93], v[100:101], off offset:1024 nt
	global_load_dwordx2 v[94:95], v[100:101], off offset:1536 nt
	global_load_dword v96, v19, s[2:3]

.LBB0_1123:
	s_cmp_lt_i32 s88, 10
	s_cselect_b64 s[0:1], -1, 0
	s_and_b64 s[6:7], s[0:1], s[2:3]
	s_andn2_b64 vcc, exec, s[6:7]
	s_cbranch_vccnz .LBB0_1140
	s_lshl_b32 s2, s66, 3
	s_lshl_b32 s0, s66, 7
	s_and_b32 s0, s0, 0xfffff000
	s_and_b32 s1, s2, 0xf8
	s_add_i32 s3, s0, 0x1000
	s_or_b32 s4, s0, s1
	s_cmpk_eq_i32 s68, 0x100
	s_cselect_b64 s[8:9], -1, 0
	s_and_b64 s[0:1], s[8:9], exec
	s_cselect_b32 s2, s4, s2
	s_cselect_b32 s12, s3, 0x8000
	s_add_i32 s13, s2, s96
	s_cmp_ge_i32 s13, s12
	s_cbranch_scc1 .LBB0_1129
	v_readlane_b32 s36, v253, 20
	v_lshlrev_b32_e32 v1, 4, v177
	v_readlane_b32 s50, v253, 34
	v_readlane_b32 s51, v253, 35
	s_nop 4
	global_load_dwordx4 v[2:5], v1, s[50:51]
	global_load_dwordx4 v[6:9], v1, s[50:51] offset:1024
	global_load_dwordx4 v[10:13], v1, s[50:51] offset:2048
	global_load_dwordx4 v[14:17], v1, s[50:51] offset:3072
	v_mbcnt_lo_u32_b32 v1, -1, 0
	v_mbcnt_hi_u32_b32 v18, -1, v1
	v_and_b32_e32 v1, 64, v18
	v_add_u32_e32 v19, 64, v1
	v_xor_b32_e32 v1, 1, v18
	v_cmp_lt_i32_e32 vcc, v1, v19
	v_xor_b32_e32 v20, 2, v18
	v_readlane_b32 s4, v252, 2
	v_cndmask_b32_e32 v1, v18, v1, vcc
	v_cmp_lt_i32_e32 vcc, v20, v19
	s_lshl_b32 s3, s68, 3
	v_readlane_b32 s5, v252, 3
	v_cndmask_b32_e32 v20, v18, v20, vcc
	v_lshlrev_b32_e32 v26, 2, v20
	v_xor_b32_e32 v20, 4, v18
	v_cmp_lt_i32_e32 vcc, v20, v19
	s_mov_b64 s[14:15], s[50:51]
	s_and_b64 s[0:1], s[8:9], exec
	v_cndmask_b32_e32 v20, v18, v20, vcc
	v_lshlrev_b32_e32 v27, 2, v20
	v_xor_b32_e32 v20, 8, v18
	v_cmp_lt_i32_e32 vcc, v20, v19
	s_cselect_b32 s14, 0x100, s3
	s_lshl_b32 s3, s66, 8
	v_cndmask_b32_e32 v20, v18, v20, vcc
	v_lshlrev_b32_e32 v28, 2, v20
	v_xor_b32_e32 v20, 16, v18
	v_cmp_lt_i32_e32 vcc, v20, v19
	s_and_b32 s3, s3, 0xffffe000
	s_add_i32 s3, s96, s3
	v_cndmask_b32_e32 v20, v18, v20, vcc
	v_lshlrev_b32_e32 v29, 2, v20
	v_xor_b32_e32 v20, 32, v18
	v_cmp_lt_i32_e32 vcc, v20, v19
	v_mov_b32_e32 v19, 0
	v_lshlrev_b32_e32 v1, 2, v1
	v_cndmask_b32_e32 v18, v18, v20, vcc
	v_lshlrev_b32_e32 v30, 2, v18
	v_lshlrev_b32_e32 v18, 3, v177
	v_lshl_add_u64 v[20:21], s[4:5], 0, v[18:19]
	v_readlane_b32 s4, v253, 52
	v_readlane_b32 s5, v253, 53
	v_cmp_eq_u32_e64 s[0:1], 0, v177
	s_mov_b32 s16, 0xffff0000
	s_waitcnt vmcnt(0)
	v_lshl_add_u64 v[22:23], s[4:5], 0, v[18:19]
	s_and_b32 s4, s66, 31
	s_lshl_b32 s4, s4, 4
	s_add_i32 s3, s3, s4
	s_sub_i32 s2, s3, s2
	s_add_i32 s15, s2, 0xf00
	v_mov_b32_e32 v31, 0x358637bd
	s_mov_b32 s17, 0xf800000
	v_mov_b32_e32 v32, 0x260
	s_movk_i32 s18, 0x7fff
	v_readlane_b32 s37, v253, 21
	v_readlane_b32 s38, v253, 22
	v_readlane_b32 s39, v253, 23
	v_readlane_b32 s40, v253, 24
	v_readlane_b32 s41, v253, 25
	v_readlane_b32 s42, v253, 26
	v_readlane_b32 s43, v253, 27
	v_readlane_b32 s44, v253, 28
	v_readlane_b32 s45, v253, 29
	v_readlane_b32 s46, v253, 30
	v_readlane_b32 s47, v253, 31
	v_readlane_b32 s48, v253, 32
	v_readlane_b32 s49, v253, 33
	s_and_b64 s[2:3], s[8:9], exec
	s_cselect_b32 s2, s15, s13
	s_ashr_i32 s3, s2, 31
	s_lshl_b64 s[4:5], s[2:3], 11
	v_lshl_add_u64 v[98:99], v[20:21], 0, s[4:5]
	v_lshl_add_u64 v[100:101], v[22:23], 0, s[4:5]
	s_lshl_b64 s[2:3], s[2:3], 2
	s_add_u32 s2, s75, s2
	s_addc_u32 s3, s69, s3
	global_load_dwordx2 v[80:81], v[98:99], off nt
	global_load_dwordx2 v[82:83], v[98:99], off offset:512 nt
	global_load_dwordx2 v[84:85], v[98:99], off offset:1024 nt
	global_load_dwordx2 v[86:87], v[98:99], off offset:1536 nt
	global_load_dwordx2 v[88:89], v[100:101], off nt
	global_load_dwordx2 v[90:91], v[100:101], off offset:512 nt
	global_load_dwordx2 v[92:93], v[100:101], off offset:1024 nt
	global_load_dwordx2 v[94:95], v[100:101], off offset:1536 nt
	global_load_dword v96, v19, s[2:3]
	s_waitcnt vmcnt(0)
	s_branch .Lrp2_body

.LBB0_1264:
	s_cmp_lt_i32 s88, 13
	s_cselect_b64 s[0:1], -1, 0
	s_and_b64 s[6:7], s[0:1], s[2:3]
	s_andn2_b64 vcc, exec, s[6:7]
	s_cbranch_vccnz .LBB0_1274
	s_lshl_b32 s12, s66, 3
	s_lshl_b32 s0, s66, 7
	s_and_b32 s0, s0, 0xfffff000
	s_and_b32 s1, s12, 0xf8
	s_add_i32 s2, s0, 0x1000
	s_or_b32 s3, s0, s1
	s_cmpk_eq_i32 s68, 0x100
	s_cselect_b64 s[8:9], -1, 0
	s_and_b64 s[0:1], s[8:9], exec
	s_cselect_b32 s13, s2, 0x8000
	s_cselect_b32 s2, s3, s12
	s_add_i32 s14, s2, s96
	s_cmp_ge_i32 s14, s13
	v_mov_b32_e32 v19, 0
	s_cbranch_scc1 .LBB0_1270
	v_lshlrev_b32_e32 v1, 4, v177
	global_load_dwordx4 v[2:5], v1, s[26:27]
	global_load_dwordx4 v[6:9], v1, s[26:27] offset:1024
	global_load_dwordx4 v[10:13], v1, s[26:27] offset:2048
	global_load_dwordx4 v[14:17], v1, s[26:27] offset:3072
	v_mbcnt_lo_u32_b32 v1, -1, 0
	v_mbcnt_hi_u32_b32 v18, -1, v1
	v_and_b32_e32 v1, 64, v18
	v_add_u32_e32 v20, 64, v1
	v_xor_b32_e32 v1, 1, v18
	v_cmp_lt_i32_e32 vcc, v1, v20
	v_xor_b32_e32 v21, 2, v18
	v_readlane_b32 s4, v252, 2
	v_cndmask_b32_e32 v1, v18, v1, vcc
	v_cmp_lt_i32_e32 vcc, v21, v20
	s_lshl_b32 s3, s68, 3
	v_readlane_b32 s5, v252, 3
	v_cndmask_b32_e32 v21, v18, v21, vcc
	v_lshlrev_b32_e32 v26, 2, v21
	v_xor_b32_e32 v21, 4, v18
	v_cmp_lt_i32_e32 vcc, v21, v20
	s_and_b64 s[0:1], s[8:9], exec
	s_cselect_b32 s15, 0x100, s3
	v_cndmask_b32_e32 v21, v18, v21, vcc
	v_lshlrev_b32_e32 v27, 2, v21
	v_xor_b32_e32 v21, 8, v18
	v_cmp_lt_i32_e32 vcc, v21, v20
	s_lshl_b32 s3, s66, 8
	s_and_b32 s3, s3, 0xffffe000
	v_cndmask_b32_e32 v21, v18, v21, vcc
	v_lshlrev_b32_e32 v28, 2, v21
	v_xor_b32_e32 v21, 16, v18
	v_cmp_lt_i32_e32 vcc, v21, v20
	s_add_i32 s3, s96, s3
	v_lshlrev_b32_e32 v1, 2, v1
	v_cndmask_b32_e32 v21, v18, v21, vcc
	v_lshlrev_b32_e32 v29, 2, v21
	v_xor_b32_e32 v21, 32, v18
	v_cmp_lt_i32_e32 vcc, v21, v20
	v_cmp_eq_u32_e64 s[0:1], 0, v177
	s_mov_b32 s17, 0xffff0000
	v_cndmask_b32_e32 v18, v18, v21, vcc
	v_lshlrev_b32_e32 v30, 2, v18
	v_lshlrev_b32_e32 v18, 3, v177
	v_lshl_add_u64 v[20:21], s[4:5], 0, v[18:19]
	v_readlane_b32 s4, v253, 52
	v_readlane_b32 s5, v253, 53
	v_mov_b32_e32 v31, 0x358637bd
	s_mov_b32 s18, 0xf800000
	s_waitcnt vmcnt(0)
	v_lshl_add_u64 v[22:23], s[4:5], 0, v[18:19]
	s_and_b32 s4, s66, 31
	s_lshl_b32 s4, s4, 4
	s_add_i32 s3, s3, s4
	s_sub_i32 s2, s3, s2
	s_add_i32 s16, s2, 0xf00
	v_mov_b32_e32 v32, 0x260
	s_movk_i32 s19, 0x7fff
	s_and_b64 s[2:3], s[8:9], exec
	s_cselect_b32 s2, s16, s14
	s_ashr_i32 s3, s2, 31
	s_lshl_b64 s[4:5], s[2:3], 11
	v_lshl_add_u64 v[98:99], v[20:21], 0, s[4:5]
	v_lshl_add_u64 v[100:101], v[22:23], 0, s[4:5]
	s_lshl_b64 s[2:3], s[2:3], 2
	s_add_u32 s2, s75, s2
	s_addc_u32 s3, s69, s3
	global_load_dwordx2 v[80:81], v[98:99], off nt
	global_load_dwordx2 v[82:83], v[98:99], off offset:512 nt
	global_load_dwordx2 v[84:85], v[98:99], off offset:1024 nt
	global_load_dwordx2 v[86:87], v[98:99], off offset:1536 nt
	global_load_dwordx2 v[88:89], v[100:101], off nt
	global_load_dwordx2 v[90:91], v[100:101], off offset:512 nt
	global_load_dwordx2 v[92:93], v[100:101], off offset:1024 nt
	global_load_dwordx2 v[94:95], v[100:101], off offset:1536 nt
	global_load_dword v96, v19, s[2:3]
	s_waitcnt vmcnt(0)
	s_branch .Lrp3_body

.Lrp3_body:
	v_mov_b32_e32 v34, v80
	v_mov_b32_e32 v35, v81
	v_mov_b32_e32 v36, v82
	v_mov_b32_e32 v37, v83
	v_mov_b32_e32 v38, v84
	v_mov_b32_e32 v39, v85
	v_mov_b32_e32 v40, v86
	v_mov_b32_e32 v41, v87
	v_mov_b32_e32 v42, v88
	v_mov_b32_e32 v43, v89
	v_mov_b32_e32 v44, v90
	v_mov_b32_e32 v45, v91
	v_mov_b32_e32 v46, v92
	v_mov_b32_e32 v47, v93
	v_mov_b32_e32 v48, v94
	v_mov_b32_e32 v49, v95
	v_mov_b32_e32 v18, v96
	s_and_b64 s[2:3], s[8:9], exec
	s_cselect_b32 s2, s16, s14
	s_ashr_i32 s3, s2, 31
	s_lshl_b64 s[4:5], s[2:3], 11
	s_lshl_b64 s[2:3], s[2:3], 2
	s_add_u32 s10, s75, s2
	v_lshl_add_u64 v[24:25], v[22:23], 0, s[4:5]
	s_addc_u32 s11, s69, s3
	s_add_i32 s2, s14, s15
	s_cmp_lt_i32 s2, s13
	s_cbranch_scc0 .Lrp3_skip
	s_sub_i32 s3, s16, s15
	s_and_b64 s[4:5], s[8:9], exec
	s_cselect_b32 s2, s3, s2
	s_ashr_i32 s3, s2, 31
	s_lshl_b64 s[4:5], s[2:3], 11
	v_lshl_add_u64 v[98:99], v[20:21], 0, s[4:5]
	v_lshl_add_u64 v[100:101], v[22:23], 0, s[4:5]
	s_lshl_b64 s[2:3], s[2:3], 2
	s_add_u32 s2, s75, s2
	s_addc_u32 s3, s69, s3
	global_load_dwordx2 v[80:81], v[98:99], off nt
	global_load_dwordx2 v[82:83], v[98:99], off offset:512 nt
	global_load_dwordx2 v[84:85], v[98:99], off offset:1024 nt
	global_load_dwordx2 v[86:87], v[98:99], off offset:1536 nt
	global_load_dwordx2 v[88:89], v[100:101], off nt
	global_load_dwordx2 v[90:91], v[100:101], off offset:512 nt
	global_load_dwordx2 v[92:93], v[100:101], off offset:1024 nt
	global_load_dwordx2 v[94:95], v[100:101], off offset:1536 nt
	global_load_dword v96, v19, s[2:3]

.LBB0_1478:
	s_lshl_b32 s2, s66, 3
	s_lshl_b32 s0, s66, 7
	s_and_b32 s0, s0, 0xfffff000
	s_and_b32 s1, s2, 0xf8
	s_add_i32 s3, s0, 0x1000
	s_or_b32 s8, s0, s1
	s_cmpk_eq_i32 s68, 0x100
	s_cselect_b64 s[6:7], -1, 0
	s_and_b64 s[0:1], s[6:7], exec
	s_cselect_b32 s2, s8, s2
	s_cselect_b32 s12, s3, 0x8000
	s_add_i32 s13, s2, s96
	s_cmp_lt_i32 s13, s12
	s_cbranch_scc0 .LBB0_1487
	v_mbcnt_lo_u32_b32 v32, -1, 0
	v_mbcnt_hi_u32_b32 v32, -1, v32
	v_and_b32_e32 v33, 64, v32
	v_add_u32_e32 v33, 64, v33
	v_xor_b32_e32 v34, 1, v32
	v_cmp_lt_i32_e32 vcc, v34, v33
	v_readlane_b32 s8, v252, 2
	s_lshl_b32 s3, s68, 3
	v_cndmask_b32_e32 v34, v32, v34, vcc
	v_lshlrev_b32_e32 v58, 2, v34
	v_xor_b32_e32 v34, 2, v32
	v_cmp_lt_i32_e32 vcc, v34, v33
	v_readlane_b32 s9, v252, 3
	s_and_b64 s[0:1], s[6:7], exec
	v_cndmask_b32_e32 v34, v32, v34, vcc
	v_lshlrev_b32_e32 v59, 2, v34
	v_xor_b32_e32 v34, 4, v32
	v_cmp_lt_i32_e32 vcc, v34, v33
	s_cselect_b32 s14, 0x100, s3
	s_lshl_b32 s3, s66, 8
	v_cndmask_b32_e32 v34, v32, v34, vcc
	v_lshlrev_b32_e32 v60, 2, v34
	v_xor_b32_e32 v34, 8, v32
	v_cmp_lt_i32_e32 vcc, v34, v33
	s_and_b32 s3, s3, 0xffffe000
	s_add_i32 s3, s96, s3
	v_cndmask_b32_e32 v34, v32, v34, vcc
	v_lshlrev_b32_e32 v61, 2, v34
	v_xor_b32_e32 v34, 16, v32
	v_cmp_lt_i32_e32 vcc, v34, v33
	v_cmp_eq_u32_e64 s[0:1], 0, v177
	s_mov_b32 s16, 0xffff0000
	v_cndmask_b32_e32 v34, v32, v34, vcc
	v_lshlrev_b32_e32 v62, 2, v34
	v_xor_b32_e32 v34, 32, v32
	v_cmp_lt_i32_e32 vcc, v34, v33
	v_mov_b32_e32 v33, 0
	v_mov_b32_e32 v39, v33
	v_cndmask_b32_e32 v32, v32, v34, vcc
	v_lshlrev_b32_e32 v63, 2, v32
	v_lshlrev_b32_e32 v32, 3, v177
	v_lshl_add_u64 v[34:35], s[8:9], 0, v[32:33]
	v_readlane_b32 s8, v253, 52
	v_readlane_b32 s9, v253, 53
	v_lshl_add_u64 v[38:39], s[76:77], 0, v[38:39]
	v_mov_b32_e32 v64, 0x358637bd
	v_lshl_add_u64 v[36:37], s[8:9], 0, v[32:33]
	s_and_b32 s8, s66, 31
	s_lshl_b32 s8, s8, 4
	s_add_i32 s3, s3, s8
	s_sub_i32 s2, s3, s2
	s_add_i32 s15, s2, 0xf00
	s_mov_b32 s17, 0xf800000
	v_mov_b32_e32 v65, 0x260
	s_movk_i32 s18, 0x7fff
	s_and_b64 s[2:3], s[6:7], exec
	s_cselect_b32 s2, s15, s13
	s_ashr_i32 s3, s2, 31
	s_lshl_b64 vcc, s[2:3], 11
	v_lshl_add_u64 v[118:119], v[34:35], 0, vcc
	v_lshl_add_u64 v[120:121], v[36:37], 0, vcc
	s_lshl_b64 s[2:3], s[2:3], 2
	s_add_u32 s2, s75, s2
	s_addc_u32 s3, s69, s3
	global_load_dwordx2 v[100:101], v[118:119], off nt
	global_load_dwordx2 v[102:103], v[118:119], off offset:512 nt
	global_load_dwordx2 v[104:105], v[118:119], off offset:1024 nt
	global_load_dwordx2 v[106:107], v[118:119], off offset:1536 nt
	global_load_dwordx2 v[108:109], v[120:121], off nt
	global_load_dwordx2 v[110:111], v[120:121], off offset:512 nt
	global_load_dwordx2 v[112:113], v[120:121], off offset:1024 nt
	global_load_dwordx2 v[114:115], v[120:121], off offset:1536 nt
	global_load_dword v116, v33, s[2:3]
	s_waitcnt vmcnt(0)
	s_branch .Lrp4_body

.Lrp4_body:
	v_mov_b32_e32 v42, v100
	v_mov_b32_e32 v43, v101
	v_mov_b32_e32 v44, v102
	v_mov_b32_e32 v45, v103
	v_mov_b32_e32 v46, v104
	v_mov_b32_e32 v47, v105
	v_mov_b32_e32 v48, v106
	v_mov_b32_e32 v49, v107
	v_mov_b32_e32 v50, v108
	v_mov_b32_e32 v51, v109
	v_mov_b32_e32 v52, v110
	v_mov_b32_e32 v53, v111
	v_mov_b32_e32 v54, v112
	v_mov_b32_e32 v55, v113
	v_mov_b32_e32 v56, v114
	v_mov_b32_e32 v57, v115
	v_mov_b32_e32 v32, v116
	s_and_b64 s[2:3], s[6:7], exec
	s_cselect_b32 s10, s15, s13
	s_ashr_i32 s11, s10, 31
	s_lshl_b64 s[2:3], s[10:11], 11
	v_lshl_add_u64 v[40:41], v[36:37], 0, s[2:3]
	s_lshl_b64 s[2:3], s[10:11], 2
	s_add_u32 s8, s75, s2
	s_addc_u32 s9, s69, s3
	s_add_i32 s2, s13, s14
	s_cmp_lt_i32 s2, s12
	s_cbranch_scc0 .Lrp4_skip
	s_sub_i32 s3, s15, s14
	s_and_b64 vcc, s[6:7], exec
	s_cselect_b32 s2, s3, s2
	s_ashr_i32 s3, s2, 31
	s_lshl_b64 vcc, s[2:3], 11
	v_lshl_add_u64 v[118:119], v[34:35], 0, vcc
	v_lshl_add_u64 v[120:121], v[36:37], 0, vcc
	s_lshl_b64 s[2:3], s[2:3], 2
	s_add_u32 s2, s75, s2
	s_addc_u32 s3, s69, s3
	global_load_dwordx2 v[100:101], v[118:119], off nt
	global_load_dwordx2 v[102:103], v[118:119], off offset:512 nt
	global_load_dwordx2 v[104:105], v[118:119], off offset:1024 nt
	global_load_dwordx2 v[106:107], v[118:119], off offset:1536 nt
	global_load_dwordx2 v[108:109], v[120:121], off nt
	global_load_dwordx2 v[110:111], v[120:121], off offset:512 nt
	global_load_dwordx2 v[112:113], v[120:121], off offset:1024 nt
	global_load_dwordx2 v[114:115], v[120:121], off offset:1536 nt
	global_load_dword v116, v33, s[2:3]
